# MFMA-LDS interleave in the SGU mixing loop: both operand fragment ds_reads issued before the first MFMA (was read-wait-MFMA-read-wait-MFMA)
# speedup vs baseline: 1.0057x; 1.0016x over previous
; #define LAS __attribute__((address_space(3)))
; __device__ __forceinline__ unsigned cvtpk(float lo, float hi) { f32x2_t v = {lo, hi}; bf16x2_t b = __builtin_convertvector(v, bf16x2_t); return __builtin_bit_cast(unsigned, b); }
; __device__ __forceinline__ float bflo(unsigned u) { return __uint_as_float(u << 16); }
; __device__ __forceinline__ float bfhi(unsigned u) { return __uint_as_float(u & 0xffff0000u); }
; __device__ __forceinline__ float geluf_(float x) { const float y = 0.7978845608028654f * (x + 0.044715f * x * x * x); return x * sigmoidf_(2.0f * y); }
; #define MFMA32(a, b, c) __builtin_amdgcn_mfma_f32_32x32x16_bf16((a), (b), (c), 0, 0, 0)
; __device__ __forceinline__ void sgu_item(LAS unsigned char* lds, const bf16* PROJ, bf16* MIX, const float* lg, const float* lb, const float* ws_, const float* bs_, int item, int tid) {
;     ...
;         for (int ks = 0; ks < 2 * (wt + 1); ++ks) { const int s0 = 16 * ks + 8 * hi;
;             const f32x4 w0 = *(const f32x4*)(wrow + s0), w1 = *(const f32x4*)(wrow + s0 + 4);
;             u32x4 pk; pk.x = cvtpk(s0 + 0 <= trow ? w0.x : 0.f, s0 + 1 <= trow ? w0.y : 0.f); pk.y = cvtpk(s0 + 2 <= trow ? w0.z : 0.f, s0 + 3 <= trow ? w0.w : 0.f);
;             pk.z = cvtpk(s0 + 4 <= trow ? w1.x : 0.f, s0 + 5 <= trow ? w1.y : 0.f); pk.w = cvtpk(s0 + 6 <= trow ? w1.z : 0.f, s0 + 7 <= trow ? w1.w : 0.f);
;             const bf16x8 wa = __builtin_bit_cast(bf16x8, pk);
; #pragma unroll
;             for (int ct = 0; ct < 2; ++ct) { const bf16x8 vb = *(LAS const bf16x8*)(vnT + (64 * wcg + 32 * ct + r32) * SGP + s0 * 2); acc[ct] = MFMA32(vb, wa, acc[ct]); } }
;         { const int t = 32 * wt + r32; const float bias = bs_[g * 128 + t]; const bf16* up = PROJ + (row0 + t) * NPROJ + 128 * g + 64 * wcg + 4 * hi; bf16* op = MIX + (row0 + t) * D + 128 * g + 64 * wcg + 4 * hi;
; #pragma unroll
;           for (int ct = 0; ct < 2; ++ct)
; #pragma unroll
;             for (int g4 = 0; g4 < 4; ++g4) { const u32x2 uw = *(const u32x2*)(up + 32 * ct + 8 * g4);
;                 const float o0 = geluf_(bflo(uw.x)) * (acc[ct][4 * g4] + bias), o1 = geluf_(bfhi(uw.x)) * (acc[ct][4 * g4 + 1] + bias), o2 = geluf_(bflo(uw.y)) * (acc[ct][4 * g4 + 2] + bias), o3 = geluf_(bfhi(uw.y)) * (acc[ct][4 * g4 + 3] + bias);
;                 u32x2 w; w.x = cvtpk(o0, o1); w.y = cvtpk(o2, o3); *(u32x2*)(op + 32 * ct + 8 * g4) = w; } }
.Lsgu_c_nopf:
	v_cndmask_b32_e32 v34, 0, v34, vcc
	v_cmp_lt_u32_e32 vcc, v40, v43
	s_nop 1
	v_cndmask_b32_e32 v35, 0, v35, vcc
	v_cvt_pk_bf16_f32 v34, v34, v35
	v_add_u32_e32 v35, 2, v40
	v_cmp_le_u32_e32 vcc, v35, v43
	s_nop 1
	v_cndmask_b32_e32 v35, 0, v36, vcc
	v_add_u32_e32 v36, 3, v40
	v_cmp_le_u32_e32 vcc, v36, v43
	s_nop 1
	v_cndmask_b32_e32 v36, 0, v37, vcc
	v_cvt_pk_bf16_f32 v35, v35, v36
	v_add_u32_e32 v36, 4, v40
	v_cmp_le_u32_e32 vcc, v36, v43
	v_add_u32_e32 v37, 5, v40
	s_nop 0
	v_cndmask_b32_e32 v36, 0, v54, vcc
	v_cmp_le_u32_e32 vcc, v37, v43
	s_nop 1
	v_cndmask_b32_e32 v37, 0, v55, vcc
	v_cvt_pk_bf16_f32 v36, v36, v37
	v_add_u32_e32 v37, 6, v40
	v_cmp_le_u32_e32 vcc, v37, v43
	v_add_u32_e32 v40, 7, v40
	s_nop 0
	v_cndmask_b32_e32 v37, 0, v56, vcc
	v_cmp_le_u32_e32 vcc, v40, v43
	s_nop 1
	v_cndmask_b32_e32 v40, 0, v57, vcc
	ds_read_b128 v[54:57], v0
	ds_read_b128 v[132:135], v0 offset:8704
	v_cvt_pk_bf16_f32 v37, v37, v40
	s_waitcnt lgkmcnt(1)
	s_nop 0
	v_mfma_f32_32x32x16_bf16 v[18:33], v[54:57], v[34:37], v[18:33]
	v_add_u32_e32 v0, 32, v0
	s_waitcnt lgkmcnt(0)
	v_mfma_f32_32x32x16_bf16 v[2:17], v[132:135], v[34:37], v[2:17]
	s_cbranch_scc0 .LBB0_364
	s_lshl_b32 s82, s2, 1
	v_lshl_add_u64 v[36:37], v[48:49], 0, s[82:83]
	global_load_dwordx2 v[116:117], v[36:37], off
	global_load_dwordx2 v[118:119], v[36:37], off offset:16
	global_load_dwordx2 v[120:121], v[36:37], off offset:32
	global_load_dwordx2 v[122:123], v[36:37], off offset:48
	global_load_dwordx2 v[124:125], v[36:37], off offset:64
	global_load_dwordx2 v[126:127], v[36:37], off offset:80
	global_load_dwordx2 v[128:129], v[36:37], off offset:96
	global_load_dwordx2 v[130:131], v[36:37], off offset:112
	v_or_b32_e32 v0, s2, v43
	v_lshl_add_u64 v[34:35], v[0:1], 2, s[14:15]
	global_load_dword v0, v[34:35], off
	v_lshl_add_u64 v[34:35], v[50:51], 0, s[82:83]
	s_add_i32 s1, s1, 1
	s_mov_b64 s[2:3], 0x10000
	v_lshl_add_u64 v[52:53], v[52:53], 0, s[2:3]
	s_cmp_eq_u32 s1, 4
	s_waitcnt vmcnt(0)
	v_mov_b32_e32 v38, v116
	v_mov_b32_e32 v39, v117
	v_lshlrev_b32_e32 v40, 16, v38
	v_and_b32_e32 v41, 0xffff0000, v38
	v_mul_f32_e32 v38, 0x3d372713, v40
	v_mul_f32_e32 v38, v38, v40
	v_mov_b32_e32 v54, v40
	v_fmac_f32_e32 v54, v38, v54
	v_mul_f32_e32 v38, 0x3f4c422a, v54
	v_add_f32_e32 v38, v38, v38
	v_mul_f32_e32 v38, 0xbfb8aa3b, v38
	v_exp_f32_e32 v38, v38
	v_mov_b32_e32 v55, v41
	s_waitcnt vmcnt(0)
	v_pk_add_f32 v[18:19], v[18:19], v[0:1] op_sel_hi:[1,0]
	v_pk_add_f32 v[20:21], v[20:21], v[0:1] op_sel_hi:[1,0]
	v_add_f32_e32 v38, 1.0, v38
	v_rcp_f32_e32 v54, v38
	v_mul_f32_e32 v38, 0x3d372713, v41
	v_mul_f32_e32 v38, v38, v41
	v_fmac_f32_e32 v55, v38, v55
	v_mul_f32_e32 v38, 0x3f4c422a, v55
	v_add_f32_e32 v38, v38, v38
	v_mul_f32_e32 v38, 0xbfb8aa3b, v38
	v_exp_f32_e32 v38, v38
	v_pk_add_f32 v[22:23], v[22:23], v[0:1] op_sel_hi:[1,0]
	v_pk_add_f32 v[2:3], v[2:3], v[0:1] op_sel_hi:[1,0]
	v_pk_add_f32 v[4:5], v[4:5], v[0:1] op_sel_hi:[1,0]
	v_add_f32_e32 v38, 1.0, v38
	v_rcp_f32_e32 v55, v38
	v_lshlrev_b32_e32 v38, 16, v39
	v_and_b32_e32 v39, 0xffff0000, v39
	v_pk_add_f32 v[6:7], v[6:7], v[0:1] op_sel_hi:[1,0]
	v_pk_mul_f32 v[40:41], v[54:55], v[40:41]
	v_mov_b32_e32 v54, v39
	v_pk_mul_f32 v[18:19], v[18:19], v[40:41]
	v_mul_f32_e32 v40, 0x3d372713, v38
	v_mul_f32_e32 v40, v40, v38
	v_mov_b32_e32 v41, v38
	v_fmac_f32_e32 v41, v40, v41
	v_mul_f32_e32 v40, 0x3f4c422a, v41
	v_mul_f32_e32 v41, 0x3d372713, v39
	v_mul_f32_e32 v41, v41, v39
	v_fmac_f32_e32 v54, v41, v54
	v_mul_f32_e32 v41, 0x3f4c422a, v54
	v_add_f32_e32 v40, v40, v40
	v_add_f32_e32 v41, v41, v41
	v_mul_f32_e32 v40, 0xbfb8aa3b, v40
	v_mul_f32_e32 v41, 0xbfb8aa3b, v41
	v_exp_f32_e32 v40, v40
	v_exp_f32_e32 v41, v41
	v_cvt_pk_bf16_f32 v18, v18, v19
	v_add_f32_e32 v40, 1.0, v40
	v_add_f32_e32 v41, 1.0, v41
	v_rcp_f32_e32 v40, v40
	v_rcp_f32_e32 v41, v41
	s_nop 0
	v_pk_mul_f32 v[38:39], v[40:41], v[38:39]
	s_nop 0
	v_pk_mul_f32 v[20:21], v[20:21], v[38:39]
	s_nop 0
	v_cvt_pk_bf16_f32 v19, v20, v21
	global_store_dwordx2 v[34:35], v[18:19], off
	v_mov_b32_e32 v18, v118
	v_mov_b32_e32 v19, v119
	v_lshlrev_b32_e32 v20, 16, v18
	v_and_b32_e32 v21, 0xffff0000, v18
	v_mul_f32_e32 v18, 0x3d372713, v20
	v_mul_f32_e32 v18, v18, v20
	v_mov_b32_e32 v38, v20
	v_fmac_f32_e32 v38, v18, v38
	v_mul_f32_e32 v18, 0x3f4c422a, v38
	v_add_f32_e32 v18, v18, v18
	v_mul_f32_e32 v18, 0xbfb8aa3b, v18
	v_exp_f32_e32 v18, v18
	v_mov_b32_e32 v39, v21
	v_add_f32_e32 v18, 1.0, v18
	v_rcp_f32_e32 v38, v18
	v_mul_f32_e32 v18, 0x3d372713, v21
	v_mul_f32_e32 v18, v18, v21
	v_fmac_f32_e32 v39, v18, v39
	v_mul_f32_e32 v18, 0x3f4c422a, v39
	v_add_f32_e32 v18, v18, v18
	v_mul_f32_e32 v18, 0xbfb8aa3b, v18
	v_exp_f32_e32 v18, v18
	s_nop 0
	v_add_f32_e32 v18, 1.0, v18
	v_rcp_f32_e32 v39, v18
	v_lshlrev_b32_e32 v18, 16, v19
	v_and_b32_e32 v19, 0xffff0000, v19
	v_pk_mul_f32 v[20:21], v[38:39], v[20:21]
	s_nop 0
	v_pk_mul_f32 v[20:21], v[22:23], v[20:21]
	v_mul_f32_e32 v22, 0x3d372713, v18
	v_mul_f32_e32 v22, v22, v18
	v_mov_b32_e32 v23, v18
	v_fmac_f32_e32 v23, v22, v23
	v_mul_f32_e32 v22, 0x3f4c422a, v23
	v_mul_f32_e32 v23, 0x3d372713, v19
	v_mul_f32_e32 v23, v23, v19
	v_mov_b32_e32 v38, v19
	v_fmac_f32_e32 v38, v23, v38
	v_mul_f32_e32 v23, 0x3f4c422a, v38
	v_add_f32_e32 v22, v22, v22
	v_add_f32_e32 v23, v23, v23
	v_mul_f32_e32 v22, 0xbfb8aa3b, v22
	v_mul_f32_e32 v23, 0xbfb8aa3b, v23
	v_exp_f32_e32 v22, v22
	v_exp_f32_e32 v23, v23
	v_cvt_pk_bf16_f32 v20, v20, v21
	v_add_f32_e32 v22, 1.0, v22
	v_add_f32_e32 v23, 1.0, v23
	v_rcp_f32_e32 v22, v22
	v_rcp_f32_e32 v23, v23
	s_nop 0
	v_pk_mul_f32 v[18:19], v[22:23], v[18:19]
	v_pk_add_f32 v[22:23], v[24:25], v[0:1] op_sel_hi:[1,0]
; __device__ __forceinline__ unsigned cvtpk(float lo, float hi) { f32x2_t v = {lo, hi}; bf16x2_t b = __builtin_convertvector(v, bf16x2_t); return __builtin_bit_cast(unsigned, b); }
; __device__ __forceinline__ float bflo(unsigned u) { return __uint_as_float(u << 16); }
; __device__ __forceinline__ float bfhi(unsigned u) { return __uint_as_float(u & 0xffff0000u); }
; __device__ __forceinline__ float geluf_(float x) { const float y = 0.7978845608028654f * (x + 0.044715f * x * x * x); return x * sigmoidf_(2.0f * y); }
; __device__ __forceinline__ void sgu_item(LAS unsigned char* lds, const bf16* PROJ, bf16* MIX, const float* lg, const float* lb, const float* ws_, const float* bs_, int item, int tid) {
;     ...
;         { const int t = 32 * wt + r32; const float bias = bs_[g * 128 + t]; const bf16* up = PROJ + (row0 + t) * NPROJ + 128 * g + 64 * wcg + 4 * hi; bf16* op = MIX + (row0 + t) * D + 128 * g + 64 * wcg + 4 * hi;
; #pragma unroll
;           for (int ct = 0; ct < 2; ++ct)
; #pragma unroll
;             for (int g4 = 0; g4 < 4; ++g4) { const u32x2 uw = *(const u32x2*)(up + 32 * ct + 8 * g4);
;                 const float o0 = geluf_(bflo(uw.x)) * (acc[ct][4 * g4] + bias), o1 = geluf_(bfhi(uw.x)) * (acc[ct][4 * g4 + 1] + bias), o2 = geluf_(bflo(uw.y)) * (acc[ct][4 * g4 + 2] + bias), o3 = geluf_(bfhi(uw.y)) * (acc[ct][4 * g4 + 3] + bias);
;                 u32x2 w; w.x = cvtpk(o0, o1); w.y = cvtpk(o2, o3); *(u32x2*)(op + 32 * ct + 8 * g4) = w; } }
	s_nop 0
	v_pk_mul_f32 v[18:19], v[22:23], v[18:19]
	s_nop 0
	v_cvt_pk_bf16_f32 v21, v18, v19
	v_mov_b32_e32 v18, v120
	v_mov_b32_e32 v19, v121
	s_nop 0
	global_store_dwordx2 v[34:35], v[20:21], off offset:16
	v_lshlrev_b32_e32 v20, 16, v18
	v_and_b32_e32 v21, 0xffff0000, v18
	v_mul_f32_e32 v18, 0x3d372713, v20
	v_mul_f32_e32 v18, v18, v20
	v_mov_b32_e32 v22, v20
	v_fmac_f32_e32 v22, v18, v22
	v_mul_f32_e32 v18, 0x3f4c422a, v22
	v_add_f32_e32 v18, v18, v18
	v_mul_f32_e32 v18, 0xbfb8aa3b, v18
	v_exp_f32_e32 v18, v18
	v_mov_b32_e32 v23, v21
	v_add_f32_e32 v18, 1.0, v18
	v_rcp_f32_e32 v22, v18
	v_mul_f32_e32 v18, 0x3d372713, v21
	v_mul_f32_e32 v18, v18, v21
	v_fmac_f32_e32 v23, v18, v23
	v_mul_f32_e32 v18, 0x3f4c422a, v23
	v_add_f32_e32 v18, v18, v18
	v_mul_f32_e32 v18, 0xbfb8aa3b, v18
	v_exp_f32_e32 v18, v18
	s_nop 0
	v_add_f32_e32 v18, 1.0, v18
	v_rcp_f32_e32 v23, v18
	v_lshlrev_b32_e32 v18, 16, v19
	v_and_b32_e32 v19, 0xffff0000, v19
	v_mov_b32_e32 v24, v19
	v_pk_mul_f32 v[20:21], v[22:23], v[20:21]
	v_pk_add_f32 v[22:23], v[26:27], v[0:1] op_sel_hi:[1,0]
	s_nop 0
	v_pk_mul_f32 v[20:21], v[22:23], v[20:21]
	v_mul_f32_e32 v22, 0x3d372713, v18
	v_mul_f32_e32 v22, v22, v18
	v_mov_b32_e32 v23, v18
	v_fmac_f32_e32 v23, v22, v23
	v_mul_f32_e32 v22, 0x3f4c422a, v23
	v_mul_f32_e32 v23, 0x3d372713, v19
	v_mul_f32_e32 v23, v23, v19
	v_fmac_f32_e32 v24, v23, v24
	v_mul_f32_e32 v23, 0x3f4c422a, v24
	v_add_f32_e32 v22, v22, v22
	v_add_f32_e32 v23, v23, v23
	v_mul_f32_e32 v22, 0xbfb8aa3b, v22
	v_mul_f32_e32 v23, 0xbfb8aa3b, v23
	v_exp_f32_e32 v22, v22
	v_exp_f32_e32 v23, v23
	v_cvt_pk_bf16_f32 v20, v20, v21
	v_add_f32_e32 v22, 1.0, v22
	v_add_f32_e32 v23, 1.0, v23
	v_rcp_f32_e32 v22, v22
	v_rcp_f32_e32 v23, v23
	s_nop 0
	v_pk_mul_f32 v[18:19], v[22:23], v[18:19]
	v_pk_add_f32 v[22:23], v[28:29], v[0:1] op_sel_hi:[1,0]
	s_nop 0
	v_pk_mul_f32 v[18:19], v[22:23], v[18:19]
	s_nop 0
	v_cvt_pk_bf16_f32 v21, v18, v19
	v_mov_b32_e32 v18, v122
	v_mov_b32_e32 v19, v123
	s_nop 0
	global_store_dwordx2 v[34:35], v[20:21], off offset:32
	v_lshlrev_b32_e32 v20, 16, v18
	v_and_b32_e32 v21, 0xffff0000, v18
	v_mul_f32_e32 v18, 0x3d372713, v20
	v_mul_f32_e32 v18, v18, v20
	v_mov_b32_e32 v22, v20
	v_fmac_f32_e32 v22, v18, v22
	v_mul_f32_e32 v18, 0x3f4c422a, v22
	v_add_f32_e32 v18, v18, v18
	v_mul_f32_e32 v18, 0xbfb8aa3b, v18
	v_exp_f32_e32 v18, v18
	v_mov_b32_e32 v23, v21
	v_add_f32_e32 v18, 1.0, v18
	v_rcp_f32_e32 v22, v18
	v_mul_f32_e32 v18, 0x3d372713, v21
	v_mul_f32_e32 v18, v18, v21
	v_fmac_f32_e32 v23, v18, v23
	v_mul_f32_e32 v18, 0x3f4c422a, v23
	v_add_f32_e32 v18, v18, v18
	v_mul_f32_e32 v18, 0xbfb8aa3b, v18
	v_exp_f32_e32 v18, v18
	s_nop 0
	v_add_f32_e32 v18, 1.0, v18
	v_rcp_f32_e32 v23, v18
	v_lshlrev_b32_e32 v18, 16, v19
	v_and_b32_e32 v19, 0xffff0000, v19
	v_mov_b32_e32 v24, v19
	v_pk_mul_f32 v[20:21], v[22:23], v[20:21]
	v_pk_add_f32 v[22:23], v[30:31], v[0:1] op_sel_hi:[1,0]
	s_nop 0
	v_pk_mul_f32 v[20:21], v[22:23], v[20:21]
	v_mul_f32_e32 v22, 0x3d372713, v18
	v_mul_f32_e32 v22, v22, v18
	v_mov_b32_e32 v23, v18
	v_fmac_f32_e32 v23, v22, v23
	v_mul_f32_e32 v22, 0x3f4c422a, v23
	v_mul_f32_e32 v23, 0x3d372713, v19
	v_mul_f32_e32 v23, v23, v19
	v_fmac_f32_e32 v24, v23, v24
	v_mul_f32_e32 v23, 0x3f4c422a, v24
	v_add_f32_e32 v22, v22, v22
	v_add_f32_e32 v23, v23, v23
	v_mul_f32_e32 v22, 0xbfb8aa3b, v22
	v_mul_f32_e32 v23, 0xbfb8aa3b, v23
	v_exp_f32_e32 v22, v22
	v_exp_f32_e32 v23, v23
	v_cvt_pk_bf16_f32 v20, v20, v21
	v_add_f32_e32 v22, 1.0, v22
	v_add_f32_e32 v23, 1.0, v23
	v_rcp_f32_e32 v22, v22
	v_rcp_f32_e32 v23, v23
	s_nop 0
	v_pk_mul_f32 v[18:19], v[22:23], v[18:19]
	v_pk_add_f32 v[22:23], v[32:33], v[0:1] op_sel_hi:[1,0]
	s_nop 0
	v_pk_mul_f32 v[18:19], v[22:23], v[18:19]
	s_nop 0
	v_cvt_pk_bf16_f32 v21, v18, v19
	v_mov_b32_e32 v18, v124
	v_mov_b32_e32 v19, v125
	s_nop 0
	global_store_dwordx2 v[34:35], v[20:21], off offset:48
	v_lshlrev_b32_e32 v20, 16, v18
	v_and_b32_e32 v21, 0xffff0000, v18
	v_mul_f32_e32 v18, 0x3d372713, v20
	v_mul_f32_e32 v18, v18, v20
	v_mov_b32_e32 v22, v20
	v_fmac_f32_e32 v22, v18, v22
	v_mul_f32_e32 v18, 0x3f4c422a, v22
	v_add_f32_e32 v18, v18, v18
	v_mul_f32_e32 v18, 0xbfb8aa3b, v18
	v_exp_f32_e32 v18, v18
	v_mov_b32_e32 v23, v21
	v_add_f32_e32 v18, 1.0, v18
	v_rcp_f32_e32 v22, v18
	v_mul_f32_e32 v18, 0x3d372713, v21
	v_mul_f32_e32 v18, v18, v21
	v_fmac_f32_e32 v23, v18, v23
	v_mul_f32_e32 v18, 0x3f4c422a, v23
	v_add_f32_e32 v18, v18, v18
	v_mul_f32_e32 v18, 0xbfb8aa3b, v18
	v_exp_f32_e32 v18, v18
	s_nop 0
	v_add_f32_e32 v18, 1.0, v18
	v_rcp_f32_e32 v23, v18
	v_lshlrev_b32_e32 v18, 16, v19
	v_and_b32_e32 v19, 0xffff0000, v19
	v_pk_mul_f32 v[20:21], v[22:23], v[20:21]
	s_nop 0
	v_pk_mul_f32 v[2:3], v[2:3], v[20:21]
	v_mul_f32_e32 v20, 0x3d372713, v18
	v_mul_f32_e32 v20, v20, v18
	v_mov_b32_e32 v21, v18
	v_fmac_f32_e32 v21, v20, v21
	v_mul_f32_e32 v20, 0x3f4c422a, v21
	v_mul_f32_e32 v21, 0x3d372713, v19
	v_mul_f32_e32 v21, v21, v19
	v_mov_b32_e32 v22, v19
	v_fmac_f32_e32 v22, v21, v22
	v_mul_f32_e32 v21, 0x3f4c422a, v22
	v_add_f32_e32 v20, v20, v20
	v_add_f32_e32 v21, v21, v21
	v_mul_f32_e32 v20, 0xbfb8aa3b, v20
	v_mul_f32_e32 v21, 0xbfb8aa3b, v21
	v_exp_f32_e32 v20, v20
	v_exp_f32_e32 v21, v21
	v_cvt_pk_bf16_f32 v2, v2, v3
	v_add_f32_e32 v20, 1.0, v20
	v_add_f32_e32 v21, 1.0, v21
	v_rcp_f32_e32 v20, v20
; __device__ __forceinline__ unsigned cvtpk(float lo, float hi) { f32x2_t v = {lo, hi}; bf16x2_t b = __builtin_convertvector(v, bf16x2_t); return __builtin_bit_cast(unsigned, b); }
; __device__ __forceinline__ float bflo(unsigned u) { return __uint_as_float(u << 16); }
; __device__ __forceinline__ float bfhi(unsigned u) { return __uint_as_float(u & 0xffff0000u); }
; __device__ __forceinline__ float geluf_(float x) { const float y = 0.7978845608028654f * (x + 0.044715f * x * x * x); return x * sigmoidf_(2.0f * y); }
; __device__ __forceinline__ void sgu_item(LAS unsigned char* lds, const bf16* PROJ, bf16* MIX, const float* lg, const float* lb, const float* ws_, const float* bs_, int item, int tid) {
;     ...
;         { const int t = 32 * wt + r32; const float bias = bs_[g * 128 + t]; const bf16* up = PROJ + (row0 + t) * NPROJ + 128 * g + 64 * wcg + 4 * hi; bf16* op = MIX + (row0 + t) * D + 128 * g + 64 * wcg + 4 * hi;
; #pragma unroll
;           for (int ct = 0; ct < 2; ++ct)
; #pragma unroll
;             for (int g4 = 0; g4 < 4; ++g4) { const u32x2 uw = *(const u32x2*)(up + 32 * ct + 8 * g4);
;                 const float o0 = geluf_(bflo(uw.x)) * (acc[ct][4 * g4] + bias), o1 = geluf_(bfhi(uw.x)) * (acc[ct][4 * g4 + 1] + bias), o2 = geluf_(bflo(uw.y)) * (acc[ct][4 * g4 + 2] + bias), o3 = geluf_(bfhi(uw.y)) * (acc[ct][4 * g4 + 3] + bias);
;                 u32x2 w; w.x = cvtpk(o0, o1); w.y = cvtpk(o2, o3); *(u32x2*)(op + 32 * ct + 8 * g4) = w; } }
;         __syncthreads();
	v_rcp_f32_e32 v21, v21
	s_nop 0
	v_pk_mul_f32 v[18:19], v[20:21], v[18:19]
	s_nop 0
	v_pk_mul_f32 v[4:5], v[4:5], v[18:19]
	s_nop 0
	v_cvt_pk_bf16_f32 v3, v4, v5
	global_store_dwordx2 v[34:35], v[2:3], off offset:64
	v_mov_b32_e32 v2, v126
	v_mov_b32_e32 v3, v127
	v_lshlrev_b32_e32 v4, 16, v2
	v_and_b32_e32 v5, 0xffff0000, v2
	v_mul_f32_e32 v2, 0x3d372713, v4
	v_mul_f32_e32 v2, v2, v4
	v_mov_b32_e32 v18, v4
	v_fmac_f32_e32 v18, v2, v18
	v_mul_f32_e32 v2, 0x3f4c422a, v18
	v_add_f32_e32 v2, v2, v2
	v_mul_f32_e32 v2, 0xbfb8aa3b, v2
	v_exp_f32_e32 v2, v2
	v_mov_b32_e32 v19, v5
	v_add_f32_e32 v2, 1.0, v2
	v_rcp_f32_e32 v18, v2
	v_mul_f32_e32 v2, 0x3d372713, v5
	v_mul_f32_e32 v2, v2, v5
	v_fmac_f32_e32 v19, v2, v19
	v_mul_f32_e32 v2, 0x3f4c422a, v19
	v_add_f32_e32 v2, v2, v2
	v_mul_f32_e32 v2, 0xbfb8aa3b, v2
	v_exp_f32_e32 v2, v2
	s_nop 0
	v_add_f32_e32 v2, 1.0, v2
	v_rcp_f32_e32 v19, v2
	v_lshlrev_b32_e32 v2, 16, v3
	v_and_b32_e32 v3, 0xffff0000, v3
	v_pk_mul_f32 v[4:5], v[18:19], v[4:5]
	s_nop 0
	v_pk_mul_f32 v[4:5], v[6:7], v[4:5]
	v_mul_f32_e32 v6, 0x3d372713, v2
	v_mul_f32_e32 v6, v6, v2
	v_mov_b32_e32 v7, v2
	v_fmac_f32_e32 v7, v6, v7
	v_mul_f32_e32 v6, 0x3f4c422a, v7
	v_mul_f32_e32 v7, 0x3d372713, v3
	v_mul_f32_e32 v7, v7, v3
	v_mov_b32_e32 v18, v3
	v_fmac_f32_e32 v18, v7, v18
	v_mul_f32_e32 v7, 0x3f4c422a, v18
	v_add_f32_e32 v6, v6, v6
	v_add_f32_e32 v7, v7, v7
	v_mul_f32_e32 v6, 0xbfb8aa3b, v6
	v_mul_f32_e32 v7, 0xbfb8aa3b, v7
	v_exp_f32_e32 v6, v6
	v_exp_f32_e32 v7, v7
	v_cvt_pk_bf16_f32 v4, v4, v5
	v_add_f32_e32 v6, 1.0, v6
	v_add_f32_e32 v7, 1.0, v7
	v_rcp_f32_e32 v6, v6
	v_rcp_f32_e32 v7, v7
	s_nop 0
	v_pk_mul_f32 v[2:3], v[6:7], v[2:3]
	v_pk_add_f32 v[6:7], v[8:9], v[0:1] op_sel_hi:[1,0]
	s_nop 0
	v_pk_mul_f32 v[2:3], v[6:7], v[2:3]
	s_nop 0
	v_cvt_pk_bf16_f32 v5, v2, v3
	v_mov_b32_e32 v2, v128
	v_mov_b32_e32 v3, v129
	s_nop 0
	global_store_dwordx2 v[34:35], v[4:5], off offset:80
	v_lshlrev_b32_e32 v4, 16, v2
	v_and_b32_e32 v5, 0xffff0000, v2
	v_mul_f32_e32 v2, 0x3d372713, v4
	v_mul_f32_e32 v2, v2, v4
	v_mov_b32_e32 v6, v4
	v_fmac_f32_e32 v6, v2, v6
	v_mul_f32_e32 v2, 0x3f4c422a, v6
	v_add_f32_e32 v2, v2, v2
	v_mul_f32_e32 v2, 0xbfb8aa3b, v2
	v_exp_f32_e32 v2, v2
	v_mov_b32_e32 v7, v5
	v_add_f32_e32 v2, 1.0, v2
	v_rcp_f32_e32 v6, v2
	v_mul_f32_e32 v2, 0x3d372713, v5
	v_mul_f32_e32 v2, v2, v5
	v_fmac_f32_e32 v7, v2, v7
	v_mul_f32_e32 v2, 0x3f4c422a, v7
	v_add_f32_e32 v2, v2, v2
	v_mul_f32_e32 v2, 0xbfb8aa3b, v2
	v_exp_f32_e32 v2, v2
	s_nop 0
	v_add_f32_e32 v2, 1.0, v2
	v_rcp_f32_e32 v7, v2
	v_lshlrev_b32_e32 v2, 16, v3
	v_and_b32_e32 v3, 0xffff0000, v3
	v_mov_b32_e32 v8, v3
	v_pk_mul_f32 v[4:5], v[6:7], v[4:5]
	v_pk_add_f32 v[6:7], v[10:11], v[0:1] op_sel_hi:[1,0]
	s_nop 0
	v_pk_mul_f32 v[4:5], v[6:7], v[4:5]
	v_mul_f32_e32 v6, 0x3d372713, v2
	v_mul_f32_e32 v6, v6, v2
	v_mov_b32_e32 v7, v2
	v_fmac_f32_e32 v7, v6, v7
	v_mul_f32_e32 v6, 0x3f4c422a, v7
	v_mul_f32_e32 v7, 0x3d372713, v3
	v_mul_f32_e32 v7, v7, v3
	v_fmac_f32_e32 v8, v7, v8
	v_mul_f32_e32 v7, 0x3f4c422a, v8
	v_add_f32_e32 v6, v6, v6
	v_add_f32_e32 v7, v7, v7
	v_mul_f32_e32 v6, 0xbfb8aa3b, v6
	v_mul_f32_e32 v7, 0xbfb8aa3b, v7
	v_exp_f32_e32 v6, v6
	v_exp_f32_e32 v7, v7
	v_cvt_pk_bf16_f32 v4, v4, v5
	v_add_f32_e32 v6, 1.0, v6
	v_add_f32_e32 v7, 1.0, v7
	v_rcp_f32_e32 v6, v6
	v_rcp_f32_e32 v7, v7
	s_nop 0
	v_pk_mul_f32 v[2:3], v[6:7], v[2:3]
	v_pk_add_f32 v[6:7], v[12:13], v[0:1] op_sel_hi:[1,0]
	s_nop 0
	v_pk_mul_f32 v[2:3], v[6:7], v[2:3]
	s_nop 0
	v_cvt_pk_bf16_f32 v5, v2, v3
	v_mov_b32_e32 v2, v130
	v_mov_b32_e32 v3, v131
	s_nop 0
	global_store_dwordx2 v[34:35], v[4:5], off offset:96
	v_lshlrev_b32_e32 v4, 16, v2
	v_and_b32_e32 v5, 0xffff0000, v2
	v_mul_f32_e32 v2, 0x3d372713, v4
	v_mul_f32_e32 v2, v2, v4
	v_mov_b32_e32 v6, v4
	v_fmac_f32_e32 v6, v2, v6
	v_mul_f32_e32 v2, 0x3f4c422a, v6
	v_add_f32_e32 v2, v2, v2
	v_mul_f32_e32 v2, 0xbfb8aa3b, v2
	v_exp_f32_e32 v2, v2
	v_mov_b32_e32 v7, v5
	v_add_f32_e32 v2, 1.0, v2
	v_rcp_f32_e32 v6, v2
	v_mul_f32_e32 v2, 0x3d372713, v5
	v_mul_f32_e32 v2, v2, v5
	v_fmac_f32_e32 v7, v2, v7
	v_mul_f32_e32 v2, 0x3f4c422a, v7
	v_add_f32_e32 v2, v2, v2
	v_mul_f32_e32 v2, 0xbfb8aa3b, v2
	v_exp_f32_e32 v2, v2
	s_nop 0
	v_add_f32_e32 v2, 1.0, v2
	v_rcp_f32_e32 v7, v2
	v_lshlrev_b32_e32 v2, 16, v3
	v_and_b32_e32 v3, 0xffff0000, v3
	v_mov_b32_e32 v8, v3
	v_pk_mul_f32 v[4:5], v[6:7], v[4:5]
	v_pk_add_f32 v[6:7], v[14:15], v[0:1] op_sel_hi:[1,0]
	s_nop 0
	v_pk_mul_f32 v[4:5], v[6:7], v[4:5]
	v_mul_f32_e32 v6, 0x3d372713, v2
	v_mul_f32_e32 v6, v6, v2
	v_mov_b32_e32 v7, v2
	v_fmac_f32_e32 v7, v6, v7
	v_mul_f32_e32 v6, 0x3f4c422a, v7
	v_mul_f32_e32 v7, 0x3d372713, v3
	v_mul_f32_e32 v7, v7, v3
	v_fmac_f32_e32 v8, v7, v8
	v_mul_f32_e32 v7, 0x3f4c422a, v8
	v_add_f32_e32 v6, v6, v6
	v_add_f32_e32 v7, v7, v7
	v_mul_f32_e32 v6, 0xbfb8aa3b, v6
	v_mul_f32_e32 v7, 0xbfb8aa3b, v7
	v_exp_f32_e32 v6, v6
	v_exp_f32_e32 v7, v7
	v_cvt_pk_bf16_f32 v4, v4, v5
	v_add_f32_e32 v6, 1.0, v6
	v_add_f32_e32 v7, 1.0, v7
	v_rcp_f32_e32 v6, v6
	v_rcp_f32_e32 v7, v7
	s_nop 0
	v_pk_mul_f32 v[2:3], v[6:7], v[2:3]
	v_pk_add_f32 v[6:7], v[16:17], v[0:1] op_sel_hi:[1,0]
	s_nop 0
	v_pk_mul_f32 v[2:3], v[6:7], v[2:3]
	s_nop 0
	v_cvt_pk_bf16_f32 v5, v2, v3
	global_store_dwordx2 v[34:35], v[4:5], off offset:112
	s_barrier
	s_cbranch_scc0 .LBB0_363
